# GEMM1 staging: each wave loads both 64B halves of its 16 rows (sibling half-line, LDS slot wid*2048+i*0x400)
# baseline (speedup 1.0000x reference)
.LBB0_303:
	s_or_b64 exec, exec, s[0:1]
	v_readlane_b32 s2, v254, 5
	v_mov_b32_e32 v2, v220
	v_readlane_b32 s3, v254, 6
	s_waitcnt lgkmcnt(0)
	s_barrier
	s_and_b64 vcc, exec, s[2:3]
	v_readfirstlane_b32 s0, v2
	s_cbranch_vccz .LBB0_364
	v_lshlrev_b32_e32 v1, 4, v2
	v_add_u32_e32 v4, 0x2000, v1
	v_ashrrev_i32_e32 v3, 31, v4
	v_lshrrev_b32_e32 v3, 22, v3
	v_add_u32_e32 v3, v4, v3
	v_ashrrev_i32_e32 v3, 10, v3
	v_mul_i32_i24_e32 v5, 0x400, v3
	v_sub_u32_e32 v4, v4, v5
	v_lshrrev_b32_e32 v5, 4, v4
	v_bitop3_b32 v5, v5, v4, 32 bitop3:0x6c
	v_ashrrev_i32_e32 v4, 31, v5
	v_lshrrev_b32_e32 v4, 26, v4
	v_add_u32_e32 v6, v5, v4
	v_lshlrev_b32_e32 v7, 3, v3
	s_mul_i32 s34, s97, 0x1a00000
	v_ashrrev_i32_e32 v4, 6, v6
	v_and_b32_e32 v7, -16, v7
	s_lshl_b64 s[2:3], s[34:35], 1
	v_readlane_b32 s4, v253, 8
	v_add_u32_e32 v7, v4, v7
	s_add_u32 s8, s4, s2
	v_and_b32_e32 v8, 3, v4
	s_mov_b32 s2, 0xfffe0
	v_lshrrev_b32_e32 v9, 2, v7
	v_lshlrev_b32_e32 v10, 1, v7
	v_and_b32_e32 v6, 0xc0, v6
	v_and_or_b32 v8, v7, s2, v8
	v_and_b32_e32 v9, 4, v9
	v_and_b32_e32 v10, 24, v10
	v_sub_u32_e32 v5, v5, v6
	v_or3_b32 v8, v8, v9, v10
	v_lshlrev_b32_e32 v9, 5, v3
	v_ashrrev_i16_sdwa v5, v223, sext(v5) dst_sel:DWORD dst_unused:UNUSED_PAD src0_sel:DWORD src1_sel:BYTE_0
	v_and_b32_e32 v9, 32, v9
	v_bfe_i32 v5, v5, 0, 16
	v_add_lshl_u32 v6, v9, v5, 1
	v_lshl_add_u32 v130, v8, 12, v6
	v_lshl_add_u32 v132, v7, 12, v6
	v_bfe_i32 v6, v2, 27, 1
	v_lshrrev_b32_e32 v6, 22, v6
	v_add_u32_e32 v6, v1, v6
	v_and_b32_e32 v6, 0xfffffc00, v6
	v_sub_u32_e32 v1, v1, v6
	v_lshrrev_b32_e32 v6, 4, v1
	v_ashrrev_i32_e32 v7, 31, v2
	v_bitop3_b32 v1, v6, v1, 32 bitop3:0x6c
	v_lshrrev_b32_e32 v7, 26, v7
	v_ashrrev_i32_e32 v6, 31, v1
	v_add_u32_e32 v7, v2, v7
	v_lshrrev_b32_e32 v6, 26, v6
	v_ashrrev_i32_e32 v7, 6, v7
	v_add_u32_e32 v8, v1, v6
	v_lshlrev_b32_e32 v9, 3, v7
	v_ashrrev_i32_e32 v6, 6, v8
	v_and_b32_e32 v9, -16, v9
	v_add_u32_e32 v9, v6, v9
	v_readlane_b32 s5, v253, 9
	v_and_b32_e32 v10, 3, v6
	v_lshrrev_b32_e32 v11, 2, v9
	v_lshlrev_b32_e32 v12, 1, v9
	v_and_b32_e32 v8, 0xc0, v8
	s_addc_u32 s9, s5, s3
	s_ashr_i32 s1, s0, 6
	v_and_or_b32 v10, v9, s2, v10
	v_and_b32_e32 v11, 4, v11
	v_and_b32_e32 v12, 24, v12
	v_sub_u32_e32 v1, v1, v8
	s_ashr_i32 s10, s0, 8
	s_lshl_b32 s19, s1, 11
	v_or3_b32 v10, v10, v11, v12
	v_lshlrev_b32_e32 v11, 5, v7
	v_ashrrev_i16_sdwa v1, v223, sext(v1) dst_sel:DWORD dst_unused:UNUSED_PAD src0_sel:DWORD src1_sel:BYTE_0
	v_readlane_b32 s2, v254, 46
	v_and_b32_e32 v11, 32, v11
	v_bfe_i32 v8, v1, 0, 16
	v_readlane_b32 s3, v254, 47
	s_add_u32 s4, s8, s2
	v_add_lshl_u32 v1, v11, v8, 1
	s_addc_u32 s5, s9, s3
	s_add_i32 s22, s19, 0
	v_lshl_add_u32 v134, v10, 12, v1
	s_add_i32 m0, s22, 0x10000
	v_lshl_add_u32 v136, v9, 12, v1
	v_and_b32_e32 v248, 63, v2
	v_lshrrev_b32_e32 v249, 2, v248
	v_and_b32_e32 v250, 3, v248
	v_lshlrev_b32_e32 v250, 4, v250
	v_lshrrev_b32_e32 v251, 5, v248
	v_lshlrev_b32_e32 v251, 5, v251
	v_xor_b32_e32 v250, v250, v251
	s_lshl_b32 s100, s1, 4
	v_add_u32_e32 v251, s100, v249
	v_lshl_add_u32 v136, v251, 12, v250
	v_add_u32_e32 v132, 64, v136
	s_lshr_b32 s100, s1, 1
	s_lshl_b32 s100, s100, 5
	s_and_b32 s101, s1, 1
	s_lshl_b32 s101, s101, 2
	s_add_u32 s100, s100, s101
	v_lshrrev_b32_e32 v251, 4, v248
	v_lshlrev_b32_e32 v251, 3, v251
	v_and_b32_e32 v249, 3, v249
	v_add3_u32 v251, v251, v249, s100
	v_lshl_add_u32 v134, v251, 12, v250
	v_add_u32_e32 v130, 64, v134
	global_load_lds_dwordx4 v134, s[4:5]
	s_add_i32 m0, s22, 0x10400
	s_add_u32 s2, s4, 0x80000
	global_load_lds_dwordx4 v130, s[4:5]
	s_addc_u32 s3, s5, 0
	s_add_i32 m0, s22, 0x14000
	s_add_i32 s23, s22, 0x400
	global_load_lds_dwordx4 v134, s[2:3]
	s_add_i32 m0, s22, 0x14400
	s_add_i32 s24, s22, 0x4000
	global_load_lds_dwordx4 v130, s[2:3]
	v_readlane_b32 s2, v254, 53
	s_mov_b32 m0, s22
	v_readlane_b32 s3, v254, 54
	s_add_i32 s25, s22, 0x4400
	s_cmp_eq_u32 s10, 1
	s_nop 2
	global_load_lds_dwordx4 v136, s[2:3]
	s_mov_b32 m0, s23
	s_nop 0
	global_load_lds_dwordx4 v132, s[2:3]
	v_readlane_b32 s2, v254, 55
	s_mov_b32 m0, s24
	v_readlane_b32 s3, v254, 56
	s_nop 4
	global_load_lds_dwordx4 v136, s[2:3]
	s_mov_b32 m0, s25
	s_nop 0
	global_load_lds_dwordx4 v132, s[2:3]
	s_cselect_b64 s[2:3], -1, 0
	s_cmp_lg_u32 s10, 1
	s_cbranch_scc1 .LBB0_306
	s_barrier
.LBB0_306:
	v_mov_b32_e32 v135, v0
	v_lshl_add_u64 v[10:11], s[4:5], 0, v[134:135]
	v_mov_b32_e32 v131, v0
	v_readlane_b32 s38, v254, 53
	s_lshl_b32 s1, s1, 5
	v_lshl_add_u64 v[12:13], s[4:5], 0, v[130:131]
	v_mov_b32_e32 v137, v0
	v_readlane_b32 s39, v254, 54
	s_and_b32 s1, s1, 0x60
	s_add_i32 m0, s22, 0x18000
	v_lshl_add_u64 v[10:11], v[10:11], 0, s[30:31]
	v_lshl_add_u64 v[14:15], s[38:39], 0, v[136:137]
	v_mov_b32_e32 v133, v0
	s_lshl_b32 s46, s10, 6
	s_lshl_b32 s16, s10, 13
	s_lshl_b32 s17, s1, 7
	s_waitcnt vmcnt(2)
	s_barrier
	global_load_lds_dwordx4 v[10:11], off
	v_lshl_add_u64 v[10:11], v[12:13], 0, s[30:31]
	s_add_i32 m0, s22, 0x18400
	s_add_i32 s47, s22, 0x8000
	s_add_i32 s48, s22, 0x8400
	v_lshl_add_u64 v[16:17], s[38:39], 0, v[132:133]
	global_load_lds_dwordx4 v[10:11], off
	v_lshl_add_u64 v[10:11], v[14:15], 0, s[30:31]
	s_mov_b32 m0, s47
	s_add_u32 s10, s4, 0x80080
	global_load_lds_dwordx4 v[10:11], off
	v_lshl_add_u64 v[10:11], v[16:17], 0, s[30:31]
	s_mov_b32 m0, s48
	s_addc_u32 s11, s5, 0
	global_load_lds_dwordx4 v[10:11], off
	s_add_i32 m0, s22, 0x1c000
	v_lshl_add_u64 v[10:11], s[10:11], 0, v[134:135]
	global_load_lds_dwordx4 v[10:11], off
	v_lshl_add_u64 v[10:11], s[10:11], 0, v[130:131]
	s_add_i32 m0, s22, 0x1c400
	v_lshrrev_b32_e32 v9, 1, v2
	global_load_lds_dwordx4 v[10:11], off
	v_and_b32_e32 v9, 24, v9
	v_and_b32_e32 v1, 15, v2
	v_lshlrev_b32_e32 v10, 1, v9
	v_lshlrev_b32_e32 v2, 2, v2
	v_lshl_or_b32 v10, v1, 6, v10
	v_and_b32_e32 v2, 32, v2
	v_bitop3_b32 v11, v10, s16, v2 bitop3:0xde
	v_bitop3_b32 v160, v10, s17, v2 bitop3:0xde
	v_lshlrev_b32_e32 v2, 15, v7
	v_and_b32_e32 v2, 0xffff0000, v2
	v_lshl_add_u32 v2, v6, 12, v2
	v_and_b32_e32 v6, 1, v7
	v_lshl_or_b32 v2, v6, 6, v2
	v_mov_b32_e32 v140, v136
	v_lshlrev_b32_e32 v2, 15, v3
	v_and_b32_e32 v2, 0xffff0000, v2
	s_waitcnt vmcnt(6)
	v_lshl_add_u32 v2, v4, 12, v2
	v_and_b32_e32 v3, 1, v3
	v_or_b32_e32 v138, s46, v1
	s_cmpk_lt_u32 s0, 0x100
	v_lshl_or_b32 v2, v3, 6, v2
	s_cselect_b64 s[10:11], -1, 0
	v_ashrrev_i32_e32 v139, 31, v138
	v_or_b32_e32 v161, s1, v9
	v_mov_b32_e32 v141, v0
	v_mov_b32_e32 v142, v132
	v_mov_b32_e32 v143, v0
	s_mov_b32 s49, 0
	v_add_u32_e32 v162, 0, v11
	v_readlane_b32 s34, v254, 45
	v_readlane_b32 s44, v254, 48
	s_mov_b64 s[0:1], s[38:39]
	s_barrier
	v_readlane_b32 s45, v254, 49
	s_branch .LBB0_309

.LBB0_312:
	s_add_u32 s4, s0, 0xfff80080
	s_addc_u32 s5, s1, -1
	s_add_i32 s54, 0, 0x10000
	s_cmp_eq_u32 s53, 28
	s_cselect_b32 s17, s37, s5
	s_cselect_b32 s16, s45, s4
	s_cselect_b32 s5, s29, s52
	s_cselect_b32 s4, s50, s51
	s_add_i32 s56, 0, 0x14000
	v_add_u32_e32 v156, s54, v160
	v_add_u32_e32 v163, s56, v160
	ds_read_b128 v[144:147], v156
	ds_read_b128 v[148:151], v156 offset:1024
	ds_read_b128 v[152:155], v156 offset:2048
	ds_read_b128 v[156:159], v156 offset:3072
	ds_read_b128 v[164:167], v163
	ds_read_b128 v[168:171], v163 offset:1024
	ds_read_b128 v[172:175], v163 offset:2048
	ds_read_b128 v[176:179], v163 offset:3072
	v_lshl_add_u64 v[238:239], s[0:1], 0, v[140:141]
	s_add_i32 m0, s22, 0xc000
	ds_read_b128 v[180:183], v162
	ds_read_b128 v[184:187], v162 offset:1024
	ds_read_b128 v[188:191], v162 offset:2048
	ds_read_b128 v[192:195], v162 offset:3072
	ds_read_b128 v[204:207], v162 offset:4096
	ds_read_b128 v[208:211], v162 offset:5120
	ds_read_b128 v[212:215], v162 offset:6144
	ds_read_b128 v[216:219], v162 offset:7168
	global_load_lds_dwordx4 v[238:239], off
	v_lshl_add_u64 v[238:239], s[0:1], 0, v[142:143]
	s_add_i32 m0, s22, 0xc400
	s_nop 0
	global_load_lds_dwordx4 v[238:239], off
	s_waitcnt vmcnt(8)
	s_waitcnt lgkmcnt(0)
	s_barrier
	s_setprio 1
	s_waitcnt lgkmcnt(0)
	v_mfma_f32_16x16x32_bf16 v[126:129], v[144:147], v[180:183], v[126:129]
	v_mfma_f32_16x16x32_bf16 v[122:125], v[152:155], v[180:183], v[122:125]
	v_mfma_f32_16x16x32_bf16 v[114:117], v[144:147], v[188:191], v[114:117]
	v_mfma_f32_16x16x32_bf16 v[106:109], v[152:155], v[188:191], v[106:109]
	v_mfma_f32_16x16x32_bf16 v[102:105], v[144:147], v[204:207], v[102:105]
	v_mfma_f32_16x16x32_bf16 v[94:97], v[152:155], v[204:207], v[94:97]
	v_mfma_f32_16x16x32_bf16 v[86:89], v[144:147], v[212:215], v[86:89]
	v_mfma_f32_16x16x32_bf16 v[78:81], v[152:155], v[212:215], v[78:81]
	v_mfma_f32_16x16x32_bf16 v[126:129], v[148:151], v[184:187], v[126:129]
	v_mfma_f32_16x16x32_bf16 v[122:125], v[156:159], v[184:187], v[122:125]
	v_mfma_f32_16x16x32_bf16 v[114:117], v[148:151], v[192:195], v[114:117]
	v_mfma_f32_16x16x32_bf16 v[106:109], v[156:159], v[192:195], v[106:109]
	v_mfma_f32_16x16x32_bf16 v[102:105], v[148:151], v[208:211], v[102:105]
	v_mfma_f32_16x16x32_bf16 v[94:97], v[156:159], v[208:211], v[94:97]
	v_mfma_f32_16x16x32_bf16 v[86:89], v[148:151], v[216:219], v[86:89]
	v_mfma_f32_16x16x32_bf16 v[78:81], v[156:159], v[216:219], v[78:81]
	s_setprio 0
	s_setprio 1
	v_mfma_f32_16x16x32_bf16 v[118:121], v[164:167], v[180:183], v[118:121]
	v_mfma_f32_16x16x32_bf16 v[110:113], v[172:175], v[180:183], v[110:113]
	v_mfma_f32_16x16x32_bf16 v[98:101], v[164:167], v[188:191], v[98:101]
	v_mfma_f32_16x16x32_bf16 v[90:93], v[172:175], v[188:191], v[90:93]
	v_mfma_f32_16x16x32_bf16 v[82:85], v[164:167], v[204:207], v[82:85]
	v_mfma_f32_16x16x32_bf16 v[74:77], v[172:175], v[204:207], v[74:77]
	v_mfma_f32_16x16x32_bf16 v[70:73], v[164:167], v[212:215], v[70:73]
	v_mfma_f32_16x16x32_bf16 v[66:69], v[172:175], v[212:215], v[66:69]
	v_mfma_f32_16x16x32_bf16 v[118:121], v[168:171], v[184:187], v[118:121]
	v_mfma_f32_16x16x32_bf16 v[110:113], v[176:179], v[184:187], v[110:113]
	v_mfma_f32_16x16x32_bf16 v[98:101], v[168:171], v[192:195], v[98:101]
	v_mfma_f32_16x16x32_bf16 v[90:93], v[176:179], v[192:195], v[90:93]
	v_mfma_f32_16x16x32_bf16 v[82:85], v[168:171], v[208:211], v[82:85]
	v_mfma_f32_16x16x32_bf16 v[74:77], v[176:179], v[208:211], v[74:77]
	v_mfma_f32_16x16x32_bf16 v[70:73], v[168:171], v[216:219], v[70:73]
	v_mfma_f32_16x16x32_bf16 v[66:69], v[176:179], v[216:219], v[66:69]
	s_setprio 0
	s_barrier
	s_add_i32 s54, s54, s19
	v_lshl_add_u64 v[238:239], s[4:5], 0, v[134:135]
	s_mov_b32 m0, s54
	ds_read_b128 v[180:183], v162 offset:16384
	ds_read_b128 v[184:187], v162 offset:17408
	ds_read_b128 v[188:191], v162 offset:18432
	ds_read_b128 v[192:195], v162 offset:19456
	ds_read_b128 v[204:207], v162 offset:20480
	ds_read_b128 v[208:211], v162 offset:21504
	ds_read_b128 v[212:215], v162 offset:22528
	ds_read_b128 v[216:219], v162 offset:23552
	global_load_lds_dwordx4 v[238:239], off
	s_add_i32 m0, s54, 0x400
	s_add_u32 s54, s4, 0x80000
	v_lshl_add_u64 v[240:241], s[4:5], 0, v[130:131]
	s_addc_u32 s55, s5, 0
	s_add_i32 s56, s56, s19
	global_load_lds_dwordx4 v[240:241], off
	v_lshl_add_u64 v[242:243], s[54:55], 0, v[134:135]
	s_mov_b32 m0, s56
	v_lshl_add_u64 v[244:245], s[16:17], 0, v[132:133]
	global_load_lds_dwordx4 v[242:243], off
	v_lshl_add_u64 v[242:243], s[54:55], 0, v[130:131]
	s_add_i32 m0, s56, 0x400
	s_nop 0
	global_load_lds_dwordx4 v[242:243], off
	v_lshl_add_u64 v[242:243], s[16:17], 0, v[136:137]
	s_mov_b32 m0, s22
	s_nop 0
	global_load_lds_dwordx4 v[242:243], off
	s_mov_b32 m0, s23
	s_nop 0
	global_load_lds_dwordx4 v[244:245], off
	s_waitcnt vmcnt(8)
	s_waitcnt lgkmcnt(0)
	s_barrier
	s_setprio 1
	s_waitcnt lgkmcnt(0)
	v_mfma_f32_16x16x32_bf16 v[62:65], v[144:147], v[180:183], v[62:65]
	v_mfma_f32_16x16x32_bf16 v[58:61], v[152:155], v[180:183], v[58:61]
	v_mfma_f32_16x16x32_bf16 v[54:57], v[144:147], v[188:191], v[54:57]
	v_mfma_f32_16x16x32_bf16 v[46:49], v[152:155], v[188:191], v[46:49]
	v_mfma_f32_16x16x32_bf16 v[38:41], v[144:147], v[204:207], v[38:41]
	v_mfma_f32_16x16x32_bf16 v[30:33], v[152:155], v[204:207], v[30:33]
	v_mfma_f32_16x16x32_bf16 v[22:25], v[144:147], v[212:215], v[22:25]
	v_mfma_f32_16x16x32_bf16 v[14:17], v[152:155], v[212:215], v[14:17]
	v_mfma_f32_16x16x32_bf16 v[62:65], v[148:151], v[184:187], v[62:65]
	v_mfma_f32_16x16x32_bf16 v[58:61], v[156:159], v[184:187], v[58:61]
	v_mfma_f32_16x16x32_bf16 v[54:57], v[148:151], v[192:195], v[54:57]
	v_mfma_f32_16x16x32_bf16 v[46:49], v[156:159], v[192:195], v[46:49]
	v_mfma_f32_16x16x32_bf16 v[38:41], v[148:151], v[208:211], v[38:41]
	v_mfma_f32_16x16x32_bf16 v[30:33], v[156:159], v[208:211], v[30:33]
	v_mfma_f32_16x16x32_bf16 v[22:25], v[148:151], v[216:219], v[22:25]
	v_mfma_f32_16x16x32_bf16 v[14:17], v[156:159], v[216:219], v[14:17]
	s_setprio 0
	s_setprio 1
	v_mfma_f32_16x16x32_bf16 v[50:53], v[164:167], v[180:183], v[50:53]
	v_mfma_f32_16x16x32_bf16 v[42:45], v[172:175], v[180:183], v[42:45]
	v_mfma_f32_16x16x32_bf16 v[34:37], v[164:167], v[188:191], v[34:37]
	v_mfma_f32_16x16x32_bf16 v[26:29], v[172:175], v[188:191], v[26:29]
	v_mfma_f32_16x16x32_bf16 v[18:21], v[164:167], v[204:207], v[18:21]
	v_mfma_f32_16x16x32_bf16 v[10:13], v[172:175], v[204:207], v[10:13]
	v_mfma_f32_16x16x32_bf16 v[6:9], v[164:167], v[212:215], v[6:9]
	v_mfma_f32_16x16x32_bf16 v[2:5], v[172:175], v[212:215], v[2:5]
	v_mfma_f32_16x16x32_bf16 v[50:53], v[168:171], v[184:187], v[50:53]
	v_mfma_f32_16x16x32_bf16 v[42:45], v[176:179], v[184:187], v[42:45]
	v_mfma_f32_16x16x32_bf16 v[34:37], v[168:171], v[192:195], v[34:37]
	v_mfma_f32_16x16x32_bf16 v[26:29], v[176:179], v[192:195], v[26:29]
	v_mfma_f32_16x16x32_bf16 v[18:21], v[168:171], v[208:211], v[18:21]
	v_mfma_f32_16x16x32_bf16 v[10:13], v[176:179], v[208:211], v[10:13]
	v_mfma_f32_16x16x32_bf16 v[6:9], v[168:171], v[216:219], v[6:9]
	v_mfma_f32_16x16x32_bf16 v[2:5], v[176:179], v[216:219], v[2:5]
	s_setprio 0
	s_barrier
	s_add_i32 s54, 0, 0x18000
	s_add_i32 s55, 0, 0x1c000
	v_add_u32_e32 v156, s54, v160
	v_add_u32_e32 v163, s55, v160
	ds_read_b128 v[144:147], v156
	ds_read_b128 v[148:151], v156 offset:1024
	ds_read_b128 v[152:155], v156 offset:2048
	ds_read_b128 v[156:159], v156 offset:3072
	ds_read_b128 v[164:167], v163
	ds_read_b128 v[168:171], v163 offset:1024
	ds_read_b128 v[172:175], v163 offset:2048
	ds_read_b128 v[176:179], v163 offset:3072
	s_add_u32 s16, s16, 0x80000
	s_addc_u32 s17, s17, 0
	s_mov_b32 m0, s24
	v_lshl_add_u64 v[246:247], s[16:17], 0, v[136:137]
	ds_read_b128 v[180:183], v162 offset:32768
	ds_read_b128 v[184:187], v162 offset:33792
	ds_read_b128 v[188:191], v162 offset:34816
	ds_read_b128 v[192:195], v162 offset:35840
	ds_read_b128 v[204:207], v162 offset:36864
	ds_read_b128 v[208:211], v162 offset:37888
	ds_read_b128 v[212:215], v162 offset:38912
	ds_read_b128 v[216:219], v162 offset:39936
	global_load_lds_dwordx4 v[246:247], off
	v_lshl_add_u64 v[246:247], s[16:17], 0, v[132:133]
	s_mov_b32 m0, s25
	s_nop 0
	global_load_lds_dwordx4 v[246:247], off
	s_waitcnt vmcnt(8)
	s_waitcnt lgkmcnt(0)
	s_barrier
	s_setprio 1
	s_waitcnt lgkmcnt(0)
	v_mfma_f32_16x16x32_bf16 v[126:129], v[144:147], v[180:183], v[126:129]
	v_mfma_f32_16x16x32_bf16 v[122:125], v[152:155], v[180:183], v[122:125]
	v_mfma_f32_16x16x32_bf16 v[114:117], v[144:147], v[188:191], v[114:117]
	v_mfma_f32_16x16x32_bf16 v[106:109], v[152:155], v[188:191], v[106:109]
	v_mfma_f32_16x16x32_bf16 v[102:105], v[144:147], v[204:207], v[102:105]
	v_mfma_f32_16x16x32_bf16 v[94:97], v[152:155], v[204:207], v[94:97]
	v_mfma_f32_16x16x32_bf16 v[86:89], v[144:147], v[212:215], v[86:89]
	v_mfma_f32_16x16x32_bf16 v[78:81], v[152:155], v[212:215], v[78:81]
	v_mfma_f32_16x16x32_bf16 v[126:129], v[148:151], v[184:187], v[126:129]
	v_mfma_f32_16x16x32_bf16 v[122:125], v[156:159], v[184:187], v[122:125]
	v_mfma_f32_16x16x32_bf16 v[114:117], v[148:151], v[192:195], v[114:117]
	v_mfma_f32_16x16x32_bf16 v[106:109], v[156:159], v[192:195], v[106:109]
	v_mfma_f32_16x16x32_bf16 v[102:105], v[148:151], v[208:211], v[102:105]
	v_mfma_f32_16x16x32_bf16 v[94:97], v[156:159], v[208:211], v[94:97]
	v_mfma_f32_16x16x32_bf16 v[86:89], v[148:151], v[216:219], v[86:89]
	v_mfma_f32_16x16x32_bf16 v[78:81], v[156:159], v[216:219], v[78:81]
	s_setprio 0
	s_setprio 1
	v_mfma_f32_16x16x32_bf16 v[118:121], v[164:167], v[180:183], v[118:121]
	v_mfma_f32_16x16x32_bf16 v[110:113], v[172:175], v[180:183], v[110:113]
	v_mfma_f32_16x16x32_bf16 v[98:101], v[164:167], v[188:191], v[98:101]
	v_mfma_f32_16x16x32_bf16 v[90:93], v[172:175], v[188:191], v[90:93]
	v_mfma_f32_16x16x32_bf16 v[82:85], v[164:167], v[204:207], v[82:85]
	v_mfma_f32_16x16x32_bf16 v[74:77], v[172:175], v[204:207], v[74:77]
	v_mfma_f32_16x16x32_bf16 v[70:73], v[164:167], v[212:215], v[70:73]
	v_mfma_f32_16x16x32_bf16 v[66:69], v[172:175], v[212:215], v[66:69]
	v_mfma_f32_16x16x32_bf16 v[118:121], v[168:171], v[184:187], v[118:121]
	v_mfma_f32_16x16x32_bf16 v[110:113], v[176:179], v[184:187], v[110:113]
	v_mfma_f32_16x16x32_bf16 v[98:101], v[168:171], v[192:195], v[98:101]
	v_mfma_f32_16x16x32_bf16 v[90:93], v[176:179], v[192:195], v[90:93]
	v_mfma_f32_16x16x32_bf16 v[82:85], v[168:171], v[208:211], v[82:85]
	v_mfma_f32_16x16x32_bf16 v[74:77], v[176:179], v[208:211], v[74:77]
	v_mfma_f32_16x16x32_bf16 v[70:73], v[168:171], v[216:219], v[70:73]
	v_mfma_f32_16x16x32_bf16 v[66:69], v[176:179], v[216:219], v[66:69]
	s_setprio 0
	s_barrier
	s_add_i32 s16, s54, s19
	v_lshl_add_u64 v[238:239], v[238:239], 0, s[30:31]
	s_mov_b32 m0, s16
	ds_read_b128 v[180:183], v162 offset:49152
	ds_read_b128 v[184:187], v162 offset:50176
	ds_read_b128 v[188:191], v162 offset:51200
	ds_read_b128 v[192:195], v162 offset:52224
	ds_read_b128 v[204:207], v162 offset:53248
	ds_read_b128 v[208:211], v162 offset:54272
	ds_read_b128 v[212:215], v162 offset:55296
	ds_read_b128 v[216:219], v162 offset:56320
	global_load_lds_dwordx4 v[238:239], off
	s_add_i32 m0, s16, 0x400
	s_add_u32 s4, s4, 0x80080
	v_lshl_add_u64 v[238:239], v[240:241], 0, s[30:31]
	s_addc_u32 s5, s5, 0
	s_add_i32 s16, s55, s19
	global_load_lds_dwordx4 v[238:239], off
	v_lshl_add_u64 v[238:239], s[4:5], 0, v[134:135]
	s_mov_b32 m0, s16
	s_nop 0
	global_load_lds_dwordx4 v[238:239], off
	v_lshl_add_u64 v[238:239], s[4:5], 0, v[130:131]
	s_add_i32 m0, s16, 0x400
	s_nop 0
	global_load_lds_dwordx4 v[238:239], off
	v_lshl_add_u64 v[238:239], v[242:243], 0, s[30:31]
	s_mov_b32 m0, s47
	s_nop 0
	global_load_lds_dwordx4 v[238:239], off
	v_lshl_add_u64 v[238:239], v[244:245], 0, s[30:31]
	s_mov_b32 m0, s48
	s_nop 0
	global_load_lds_dwordx4 v[238:239], off
	s_waitcnt vmcnt(8)
	s_waitcnt lgkmcnt(0)
	s_barrier
	s_setprio 1
	s_waitcnt lgkmcnt(0)
	v_mfma_f32_16x16x32_bf16 v[62:65], v[144:147], v[180:183], v[62:65]
	v_mfma_f32_16x16x32_bf16 v[58:61], v[152:155], v[180:183], v[58:61]
	v_mfma_f32_16x16x32_bf16 v[54:57], v[144:147], v[188:191], v[54:57]
	v_mfma_f32_16x16x32_bf16 v[46:49], v[152:155], v[188:191], v[46:49]
	v_mfma_f32_16x16x32_bf16 v[38:41], v[144:147], v[204:207], v[38:41]
	v_mfma_f32_16x16x32_bf16 v[30:33], v[152:155], v[204:207], v[30:33]
	v_mfma_f32_16x16x32_bf16 v[22:25], v[144:147], v[212:215], v[22:25]
	v_mfma_f32_16x16x32_bf16 v[14:17], v[152:155], v[212:215], v[14:17]
	v_mfma_f32_16x16x32_bf16 v[62:65], v[148:151], v[184:187], v[62:65]
	v_mfma_f32_16x16x32_bf16 v[58:61], v[156:159], v[184:187], v[58:61]
	v_mfma_f32_16x16x32_bf16 v[54:57], v[148:151], v[192:195], v[54:57]
	v_mfma_f32_16x16x32_bf16 v[46:49], v[156:159], v[192:195], v[46:49]
	v_mfma_f32_16x16x32_bf16 v[38:41], v[148:151], v[208:211], v[38:41]
	v_mfma_f32_16x16x32_bf16 v[30:33], v[156:159], v[208:211], v[30:33]
	v_mfma_f32_16x16x32_bf16 v[22:25], v[148:151], v[216:219], v[22:25]
	v_mfma_f32_16x16x32_bf16 v[14:17], v[156:159], v[216:219], v[14:17]
	s_setprio 0
	s_setprio 1
	v_mfma_f32_16x16x32_bf16 v[50:53], v[164:167], v[180:183], v[50:53]
	v_mfma_f32_16x16x32_bf16 v[42:45], v[172:175], v[180:183], v[42:45]
	v_mfma_f32_16x16x32_bf16 v[34:37], v[164:167], v[188:191], v[34:37]
	v_mfma_f32_16x16x32_bf16 v[26:29], v[172:175], v[188:191], v[26:29]
	v_mfma_f32_16x16x32_bf16 v[18:21], v[164:167], v[204:207], v[18:21]
	v_mfma_f32_16x16x32_bf16 v[10:13], v[172:175], v[204:207], v[10:13]
	v_mfma_f32_16x16x32_bf16 v[6:9], v[164:167], v[212:215], v[6:9]
	v_mfma_f32_16x16x32_bf16 v[2:5], v[172:175], v[212:215], v[2:5]
	v_mfma_f32_16x16x32_bf16 v[50:53], v[168:171], v[184:187], v[50:53]
	v_mfma_f32_16x16x32_bf16 v[42:45], v[176:179], v[184:187], v[42:45]
	v_mfma_f32_16x16x32_bf16 v[34:37], v[168:171], v[192:195], v[34:37]
	v_mfma_f32_16x16x32_bf16 v[26:29], v[176:179], v[192:195], v[26:29]
	v_mfma_f32_16x16x32_bf16 v[18:21], v[168:171], v[208:211], v[18:21]
	v_mfma_f32_16x16x32_bf16 v[10:13], v[176:179], v[208:211], v[10:13]
	v_mfma_f32_16x16x32_bf16 v[6:9], v[168:171], v[216:219], v[6:9]
	v_mfma_f32_16x16x32_bf16 v[2:5], v[176:179], v[216:219], v[2:5]
	s_setprio 0
	s_barrier
	s_add_i32 s53, s53, 2
	s_add_u32 s0, s0, 0x100
	s_addc_u32 s1, s1, 0
	s_add_u32 s51, s51, 0x100
	s_addc_u32 s52, s52, 0
	s_cmp_gt_u32 s53, 29
	s_cbranch_scc0 .LBB0_312
	s_and_b64 vcc, exec, s[10:11]
	s_cbranch_vccz .LBB0_315
	s_barrier
